# v6 + mixpre (conv) workgroup->row-block remap made XCD-contiguous so +-64-row re-reads hit the same L2
# speedup vs baseline: 1.0049x; 1.0049x over previous
.LBB0_15:
	s_mov_b64 s[80:81], s[66:67]
	v_mov_b32_e32 v186, v236
	s_mov_b32 s64, s62
	s_load_dword s75, s[66:67], 0x108
	s_waitcnt lgkmcnt(0)
	s_load_dwordx2 s[78:79], s[80:81], 0xf8
	s_memrealtime s[4:5]
	v_writelane_b32 v255, s2, 22
	s_cmp_eq_u32 s2, 3
	s_cbranch_scc1 .Lxr_do
	s_cmp_eq_u32 s2, 14
	s_cbranch_scc0 .Lxr_done
.Lxr_do:
	s_and_b32 s100, s62, 7
	s_lshl_b32 s100, s100, 5
	s_lshr_b32 s64, s62, 3
	s_add_u32 s64, s64, s100
